# hgrn pass2 carry-in loop: 24 loads per segment in flight with rolling prefetch instead of 16 serialized flat_load round trips
# speedup vs baseline: 1.0048x; 1.0048x over previous
; template <bool FULL>
; DI void hgrn_pass(const Params& p, const int j, char* lds) {
;     ...
;         if (FULL) {
;             for (int i = 0; i < seg; ++i) {
;                 const bf16_t* U = UB + ((size_t)(bh * 8 + i) * 4 + w) * 4096 + lane * 16;
;                 const float* D = DB + (size_t)(bh * 8 + i) * 128;
; #pragma unroll
;                 for (int kt = 0; kt < 4; ++kt) {
;                     const u32x4 u0 = *(const u32x4*)(U + kt * 1024), u1 = *(const u32x4*)(U + kt * 1024 + 8);
; #pragma unroll
;                     for (int g = 0; g < 4; ++g) { const f32x4 dv = *(const f32x4*)(D + 32 * kt + 8 * g + 4 * hh);
;                         const unsigned w0 = (g < 2) ? u0[2 * g] : u1[2 * (g - 2)], w1 = (g < 2) ? u0[2 * g + 1] : u1[2 * (g - 2) + 1];
;                         S[kt][4 * g + 0] = S[kt][4 * g + 0] * dv[0] + __uint_as_float(w0 << 16);
;                         S[kt][4 * g + 1] = S[kt][4 * g + 1] * dv[1] + __uint_as_float(w0 & 0xffff0000u);
;                         S[kt][4 * g + 2] = S[kt][4 * g + 2] * dv[2] + __uint_as_float(w1 << 16);
;                         S[kt][4 * g + 3] = S[kt][4 * g + 3] * dv[3] + __uint_as_float(w1 & 0xffff0000u); }
;                 }
;             }
;         }
.Lhc_top:
	v_readfirstlane_b32 s66, v81
	v_lshl_add_u64 v[46:47], s[68:69], 0, v[36:37]
	v_lshl_add_u64 v[88:89], s[68:69], 0, v[34:35]
	s_mov_b64 vcc, 0x14681000
	s_nop 0
	v_lshl_add_u64 v[86:87], v[46:47], 0, vcc
	s_mov_b64 vcc, 0x14682000
	s_nop 0
	v_lshl_add_u64 v[46:47], v[46:47], 0, vcc
	s_mov_b64 vcc, 0x15681000
	s_nop 0
	v_lshl_add_u64 v[88:89], v[88:89], 0, vcc
	global_load_dwordx4 v[214:217], v[86:87], off
	global_load_dwordx4 v[218:221], v[86:87], off offset:16
	global_load_dwordx4 v[222:225], v[88:89], off
	global_load_dwordx4 v[226:229], v[88:89], off offset:32
	global_load_dwordx4 v[230:233], v[88:89], off offset:64
	global_load_dwordx4 v[234:237], v[88:89], off offset:96
	global_load_dwordx4 v[238:241], v[86:87], off offset:2048
	global_load_dwordx4 v[242:245], v[86:87], off offset:2064
	global_load_dwordx4 v[246:249], v[88:89], off offset:128
	global_load_dwordx4 v[250:253], v[88:89], off offset:160
	global_load_dwordx4 v[94:97], v[88:89], off offset:192
	global_load_dwordx4 v[98:101], v[88:89], off offset:224
	global_load_dwordx4 v[102:105], v[46:47], off
	global_load_dwordx4 v[110:113], v[46:47], off offset:16
	global_load_dwordx4 v[114:117], v[88:89], off offset:256
	global_load_dwordx4 v[118:121], v[88:89], off offset:288
	global_load_dwordx4 v[122:125], v[88:89], off offset:320
	global_load_dwordx4 v[126:129], v[88:89], off offset:352
	global_load_dwordx4 v[172:175], v[46:47], off offset:2048
	global_load_dwordx4 v[176:179], v[46:47], off offset:2064
	global_load_dwordx4 v[180:183], v[88:89], off offset:384
	global_load_dwordx4 v[38:41], v[88:89], off offset:416
	global_load_dwordx4 v[42:45], v[88:89], off offset:448
	global_load_dwordx4 v[82:85], v[88:89], off offset:480
	s_mov_b64 vcc, 0x8000
	s_nop 0
	v_lshl_add_u64 v[86:87], v[86:87], 0, vcc
	v_lshl_add_u64 v[46:47], v[46:47], 0, vcc
	s_mov_b64 vcc, 0x200
	s_nop 0
	v_lshl_add_u64 v[88:89], v[88:89], 0, vcc
.Lhc_loop:
	s_cmp_eq_u32 s66, 1
	s_cbranch_scc1 .Lhc_last
	s_waitcnt vmcnt(18)
	v_lshlrev_b32_e32 v90, 16, v214
	v_and_b32_e32 v91, 0xffff0000, v214
	v_pk_fma_f32 v[0:1], v[0:1], v[222:223], v[90:91]
	v_lshlrev_b32_e32 v106, 16, v215
	v_and_b32_e32 v107, 0xffff0000, v215
	v_pk_fma_f32 v[2:3], v[2:3], v[224:225], v[106:107]
	v_lshlrev_b32_e32 v130, 16, v216
	v_and_b32_e32 v131, 0xffff0000, v216
	v_pk_fma_f32 v[4:5], v[4:5], v[226:227], v[130:131]
	v_lshlrev_b32_e32 v90, 16, v217
	v_and_b32_e32 v91, 0xffff0000, v217
	v_pk_fma_f32 v[6:7], v[6:7], v[228:229], v[90:91]
	v_lshlrev_b32_e32 v106, 16, v218
	v_and_b32_e32 v107, 0xffff0000, v218
	v_pk_fma_f32 v[8:9], v[8:9], v[230:231], v[106:107]
	v_lshlrev_b32_e32 v130, 16, v219
	v_and_b32_e32 v131, 0xffff0000, v219
	v_pk_fma_f32 v[10:11], v[10:11], v[232:233], v[130:131]
	v_lshlrev_b32_e32 v90, 16, v220
	v_and_b32_e32 v91, 0xffff0000, v220
	v_pk_fma_f32 v[12:13], v[12:13], v[234:235], v[90:91]
	v_lshlrev_b32_e32 v106, 16, v221
	v_and_b32_e32 v107, 0xffff0000, v221
	v_pk_fma_f32 v[14:15], v[14:15], v[236:237], v[106:107]
	global_load_dwordx4 v[214:217], v[86:87], off
	global_load_dwordx4 v[218:221], v[86:87], off offset:16
	global_load_dwordx4 v[222:225], v[88:89], off
	global_load_dwordx4 v[226:229], v[88:89], off offset:32
	global_load_dwordx4 v[230:233], v[88:89], off offset:64
	global_load_dwordx4 v[234:237], v[88:89], off offset:96
	s_waitcnt vmcnt(18)
	v_lshlrev_b32_e32 v130, 16, v238
	v_and_b32_e32 v131, 0xffff0000, v238
	v_pk_fma_f32 v[16:17], v[16:17], v[246:247], v[130:131]
	v_lshlrev_b32_e32 v90, 16, v239
	v_and_b32_e32 v91, 0xffff0000, v239
	v_pk_fma_f32 v[18:19], v[18:19], v[248:249], v[90:91]
	v_lshlrev_b32_e32 v106, 16, v240
	v_and_b32_e32 v107, 0xffff0000, v240
	v_pk_fma_f32 v[20:21], v[20:21], v[250:251], v[106:107]
	v_lshlrev_b32_e32 v130, 16, v241
	v_and_b32_e32 v131, 0xffff0000, v241
	v_pk_fma_f32 v[22:23], v[22:23], v[252:253], v[130:131]
	v_lshlrev_b32_e32 v90, 16, v242
	v_and_b32_e32 v91, 0xffff0000, v242
	v_pk_fma_f32 v[24:25], v[24:25], v[94:95], v[90:91]
	v_lshlrev_b32_e32 v106, 16, v243
	v_and_b32_e32 v107, 0xffff0000, v243
	v_pk_fma_f32 v[26:27], v[26:27], v[96:97], v[106:107]
	v_lshlrev_b32_e32 v130, 16, v244
	v_and_b32_e32 v131, 0xffff0000, v244
	v_pk_fma_f32 v[28:29], v[28:29], v[98:99], v[130:131]
	v_lshlrev_b32_e32 v90, 16, v245
	v_and_b32_e32 v91, 0xffff0000, v245
	v_pk_fma_f32 v[30:31], v[30:31], v[100:101], v[90:91]
	global_load_dwordx4 v[238:241], v[86:87], off offset:2048
	global_load_dwordx4 v[242:245], v[86:87], off offset:2064
	global_load_dwordx4 v[246:249], v[88:89], off offset:128
	global_load_dwordx4 v[250:253], v[88:89], off offset:160
	global_load_dwordx4 v[94:97], v[88:89], off offset:192
	global_load_dwordx4 v[98:101], v[88:89], off offset:224
	s_waitcnt vmcnt(18)
	v_lshlrev_b32_e32 v106, 16, v102
	v_and_b32_e32 v107, 0xffff0000, v102
	v_pk_fma_f32 v[48:49], v[48:49], v[114:115], v[106:107]
	v_lshlrev_b32_e32 v130, 16, v103
	v_and_b32_e32 v131, 0xffff0000, v103
	v_pk_fma_f32 v[50:51], v[50:51], v[116:117], v[130:131]
	v_lshlrev_b32_e32 v90, 16, v104
	v_and_b32_e32 v91, 0xffff0000, v104
	v_pk_fma_f32 v[52:53], v[52:53], v[118:119], v[90:91]
	v_lshlrev_b32_e32 v106, 16, v105
	v_and_b32_e32 v107, 0xffff0000, v105
	v_pk_fma_f32 v[54:55], v[54:55], v[120:121], v[106:107]
	v_lshlrev_b32_e32 v130, 16, v110
	v_and_b32_e32 v131, 0xffff0000, v110
	v_pk_fma_f32 v[56:57], v[56:57], v[122:123], v[130:131]
	v_lshlrev_b32_e32 v90, 16, v111
	v_and_b32_e32 v91, 0xffff0000, v111
	v_pk_fma_f32 v[58:59], v[58:59], v[124:125], v[90:91]
	v_lshlrev_b32_e32 v106, 16, v112
	v_and_b32_e32 v107, 0xffff0000, v112
	v_pk_fma_f32 v[60:61], v[60:61], v[126:127], v[106:107]
	v_lshlrev_b32_e32 v130, 16, v113
	v_and_b32_e32 v131, 0xffff0000, v113
	v_pk_fma_f32 v[62:63], v[62:63], v[128:129], v[130:131]
	global_load_dwordx4 v[102:105], v[46:47], off
	global_load_dwordx4 v[110:113], v[46:47], off offset:16
	global_load_dwordx4 v[114:117], v[88:89], off offset:256
	global_load_dwordx4 v[118:121], v[88:89], off offset:288
	global_load_dwordx4 v[122:125], v[88:89], off offset:320
	global_load_dwordx4 v[126:129], v[88:89], off offset:352
	s_waitcnt vmcnt(18)
; template <bool FULL>
; DI void hgrn_pass(const Params& p, const int j, char* lds) {
;     ...
;         if (FULL) {
;             for (int i = 0; i < seg; ++i) {
;                 const bf16_t* U = UB + ((size_t)(bh * 8 + i) * 4 + w) * 4096 + lane * 16;
;                 const float* D = DB + (size_t)(bh * 8 + i) * 128;
; #pragma unroll
;                 for (int kt = 0; kt < 4; ++kt) {
;                     const u32x4 u0 = *(const u32x4*)(U + kt * 1024), u1 = *(const u32x4*)(U + kt * 1024 + 8);
; #pragma unroll
;                     for (int g = 0; g < 4; ++g) { const f32x4 dv = *(const f32x4*)(D + 32 * kt + 8 * g + 4 * hh);
;                         const unsigned w0 = (g < 2) ? u0[2 * g] : u1[2 * (g - 2)], w1 = (g < 2) ? u0[2 * g + 1] : u1[2 * (g - 2) + 1];
;                         S[kt][4 * g + 0] = S[kt][4 * g + 0] * dv[0] + __uint_as_float(w0 << 16);
;                         S[kt][4 * g + 1] = S[kt][4 * g + 1] * dv[1] + __uint_as_float(w0 & 0xffff0000u);
;                         S[kt][4 * g + 2] = S[kt][4 * g + 2] * dv[2] + __uint_as_float(w1 << 16);
;                         S[kt][4 * g + 3] = S[kt][4 * g + 3] * dv[3] + __uint_as_float(w1 & 0xffff0000u); }
;                 }
;             }
;         }
	v_lshlrev_b32_e32 v90, 16, v172
	v_and_b32_e32 v91, 0xffff0000, v172
	v_pk_fma_f32 v[64:65], v[64:65], v[180:181], v[90:91]
	v_lshlrev_b32_e32 v106, 16, v173
	v_and_b32_e32 v107, 0xffff0000, v173
	v_pk_fma_f32 v[66:67], v[66:67], v[182:183], v[106:107]
	v_lshlrev_b32_e32 v130, 16, v174
	v_and_b32_e32 v131, 0xffff0000, v174
	v_pk_fma_f32 v[68:69], v[68:69], v[38:39], v[130:131]
	v_lshlrev_b32_e32 v90, 16, v175
	v_and_b32_e32 v91, 0xffff0000, v175
	v_pk_fma_f32 v[70:71], v[70:71], v[40:41], v[90:91]
	v_lshlrev_b32_e32 v106, 16, v176
	v_and_b32_e32 v107, 0xffff0000, v176
	v_pk_fma_f32 v[72:73], v[72:73], v[42:43], v[106:107]
	v_lshlrev_b32_e32 v130, 16, v177
	v_and_b32_e32 v131, 0xffff0000, v177
	v_pk_fma_f32 v[74:75], v[74:75], v[44:45], v[130:131]
	v_lshlrev_b32_e32 v90, 16, v178
	v_and_b32_e32 v91, 0xffff0000, v178
	v_pk_fma_f32 v[76:77], v[76:77], v[82:83], v[90:91]
	v_lshlrev_b32_e32 v106, 16, v179
	v_and_b32_e32 v107, 0xffff0000, v179
	v_pk_fma_f32 v[78:79], v[78:79], v[84:85], v[106:107]
	global_load_dwordx4 v[172:175], v[46:47], off offset:2048
	global_load_dwordx4 v[176:179], v[46:47], off offset:2064
	global_load_dwordx4 v[180:183], v[88:89], off offset:384
	global_load_dwordx4 v[38:41], v[88:89], off offset:416
	global_load_dwordx4 v[42:45], v[88:89], off offset:448
	global_load_dwordx4 v[82:85], v[88:89], off offset:480
	s_mov_b64 vcc, 0x8000
	s_nop 0
	v_lshl_add_u64 v[86:87], v[86:87], 0, vcc
	v_lshl_add_u64 v[46:47], v[46:47], 0, vcc
	s_mov_b64 vcc, 0x200
	s_nop 0
	v_lshl_add_u64 v[88:89], v[88:89], 0, vcc
	s_sub_u32 s66, s66, 1
	s_branch .Lhc_loop
.Lhc_last:
	s_waitcnt vmcnt(18)
	v_lshlrev_b32_e32 v130, 16, v214
	v_and_b32_e32 v131, 0xffff0000, v214
	v_pk_fma_f32 v[0:1], v[0:1], v[222:223], v[130:131]
	v_lshlrev_b32_e32 v90, 16, v215
	v_and_b32_e32 v91, 0xffff0000, v215
	v_pk_fma_f32 v[2:3], v[2:3], v[224:225], v[90:91]
	v_lshlrev_b32_e32 v106, 16, v216
	v_and_b32_e32 v107, 0xffff0000, v216
	v_pk_fma_f32 v[4:5], v[4:5], v[226:227], v[106:107]
	v_lshlrev_b32_e32 v130, 16, v217
	v_and_b32_e32 v131, 0xffff0000, v217
	v_pk_fma_f32 v[6:7], v[6:7], v[228:229], v[130:131]
	v_lshlrev_b32_e32 v90, 16, v218
	v_and_b32_e32 v91, 0xffff0000, v218
	v_pk_fma_f32 v[8:9], v[8:9], v[230:231], v[90:91]
	v_lshlrev_b32_e32 v106, 16, v219
	v_and_b32_e32 v107, 0xffff0000, v219
	v_pk_fma_f32 v[10:11], v[10:11], v[232:233], v[106:107]
	v_lshlrev_b32_e32 v130, 16, v220
	v_and_b32_e32 v131, 0xffff0000, v220
	v_pk_fma_f32 v[12:13], v[12:13], v[234:235], v[130:131]
	v_lshlrev_b32_e32 v90, 16, v221
	v_and_b32_e32 v91, 0xffff0000, v221
	v_pk_fma_f32 v[14:15], v[14:15], v[236:237], v[90:91]
	s_waitcnt vmcnt(12)
	v_lshlrev_b32_e32 v106, 16, v238
	v_and_b32_e32 v107, 0xffff0000, v238
	v_pk_fma_f32 v[16:17], v[16:17], v[246:247], v[106:107]
	v_lshlrev_b32_e32 v130, 16, v239
	v_and_b32_e32 v131, 0xffff0000, v239
	v_pk_fma_f32 v[18:19], v[18:19], v[248:249], v[130:131]
	v_lshlrev_b32_e32 v90, 16, v240
	v_and_b32_e32 v91, 0xffff0000, v240
	v_pk_fma_f32 v[20:21], v[20:21], v[250:251], v[90:91]
	v_lshlrev_b32_e32 v106, 16, v241
	v_and_b32_e32 v107, 0xffff0000, v241
	v_pk_fma_f32 v[22:23], v[22:23], v[252:253], v[106:107]
	v_lshlrev_b32_e32 v130, 16, v242
	v_and_b32_e32 v131, 0xffff0000, v242
	v_pk_fma_f32 v[24:25], v[24:25], v[94:95], v[130:131]
	v_lshlrev_b32_e32 v90, 16, v243
	v_and_b32_e32 v91, 0xffff0000, v243
	v_pk_fma_f32 v[26:27], v[26:27], v[96:97], v[90:91]
	v_lshlrev_b32_e32 v106, 16, v244
	v_and_b32_e32 v107, 0xffff0000, v244
	v_pk_fma_f32 v[28:29], v[28:29], v[98:99], v[106:107]
	v_lshlrev_b32_e32 v130, 16, v245
	v_and_b32_e32 v131, 0xffff0000, v245
	v_pk_fma_f32 v[30:31], v[30:31], v[100:101], v[130:131]
	s_waitcnt vmcnt(6)
	v_lshlrev_b32_e32 v90, 16, v102
	v_and_b32_e32 v91, 0xffff0000, v102
	v_pk_fma_f32 v[48:49], v[48:49], v[114:115], v[90:91]
	v_lshlrev_b32_e32 v106, 16, v103
	v_and_b32_e32 v107, 0xffff0000, v103
	v_pk_fma_f32 v[50:51], v[50:51], v[116:117], v[106:107]
	v_lshlrev_b32_e32 v130, 16, v104
	v_and_b32_e32 v131, 0xffff0000, v104
	v_pk_fma_f32 v[52:53], v[52:53], v[118:119], v[130:131]
	v_lshlrev_b32_e32 v90, 16, v105
	v_and_b32_e32 v91, 0xffff0000, v105
	v_pk_fma_f32 v[54:55], v[54:55], v[120:121], v[90:91]
	v_lshlrev_b32_e32 v106, 16, v110
	v_and_b32_e32 v107, 0xffff0000, v110
	v_pk_fma_f32 v[56:57], v[56:57], v[122:123], v[106:107]
	v_lshlrev_b32_e32 v130, 16, v111
	v_and_b32_e32 v131, 0xffff0000, v111
	v_pk_fma_f32 v[58:59], v[58:59], v[124:125], v[130:131]
	v_lshlrev_b32_e32 v90, 16, v112
	v_and_b32_e32 v91, 0xffff0000, v112
	v_pk_fma_f32 v[60:61], v[60:61], v[126:127], v[90:91]
	v_lshlrev_b32_e32 v106, 16, v113
	v_and_b32_e32 v107, 0xffff0000, v113
	v_pk_fma_f32 v[62:63], v[62:63], v[128:129], v[106:107]
	s_waitcnt vmcnt(0)
	v_lshlrev_b32_e32 v130, 16, v172
	v_and_b32_e32 v131, 0xffff0000, v172
	v_pk_fma_f32 v[64:65], v[64:65], v[180:181], v[130:131]
	v_lshlrev_b32_e32 v90, 16, v173
	v_and_b32_e32 v91, 0xffff0000, v173
	v_pk_fma_f32 v[66:67], v[66:67], v[182:183], v[90:91]
	v_lshlrev_b32_e32 v106, 16, v174
	v_and_b32_e32 v107, 0xffff0000, v174
	v_pk_fma_f32 v[68:69], v[68:69], v[38:39], v[106:107]
	v_lshlrev_b32_e32 v130, 16, v175
	v_and_b32_e32 v131, 0xffff0000, v175
	v_pk_fma_f32 v[70:71], v[70:71], v[40:41], v[130:131]
	v_lshlrev_b32_e32 v90, 16, v176
	v_and_b32_e32 v91, 0xffff0000, v176
	v_pk_fma_f32 v[72:73], v[72:73], v[42:43], v[90:91]
	v_lshlrev_b32_e32 v106, 16, v177
	v_and_b32_e32 v107, 0xffff0000, v177
	v_pk_fma_f32 v[74:75], v[74:75], v[44:45], v[106:107]
	v_lshlrev_b32_e32 v130, 16, v178
	v_and_b32_e32 v131, 0xffff0000, v178
	v_pk_fma_f32 v[76:77], v[76:77], v[82:83], v[130:131]
	v_lshlrev_b32_e32 v90, 16, v179
	v_and_b32_e32 v91, 0xffff0000, v179
	v_pk_fma_f32 v[78:79], v[78:79], v[84:85], v[90:91]
